# grid barrier: waiting workgroups poll the cross-XCD arrival counter until it reaches (gen+1)*nXCD; no separate release hop
# baseline (speedup 1.0000x reference)
; __device__ __forceinline__ unsigned xb_ld(unsigned* p)              { return __hip_atomic_load(p, __ATOMIC_RELAXED, __HIP_MEMORY_SCOPE_AGENT); }
; __device__ __forceinline__ unsigned xb_add(unsigned* p, unsigned v) { return __hip_atomic_fetch_add(p, v, __ATOMIC_RELAXED, __HIP_MEMORY_SCOPE_AGENT); }
; #define XB_SPIN(cond, bar) do { unsigned _sp = 0; while (cond) { __builtin_amdgcn_s_sleep(1); \
;     if ((++_sp & 255u) == 0u) { if (xb_ld(&(bar)[XB_TMO])) break; if (_sp > XB_SPIN_CAP) { atomicAdd(&(bar)[XB_TMO], 1u); break; } } } } while (0)
; __device__ __forceinline__ void xcd_barrier(const XcdBarrier& b) {
;     ...
;         const unsigned old = xb_add(&bar[XB_XSUB(b.x)], 1u);
;         const unsigned gen = old / nloc;
;         if (old + 1u == (gen + 1u) * nloc) {
;             __builtin_amdgcn_fence(__ATOMIC_RELEASE, "agent");
;             asm volatile("s_waitcnt vmcnt(0)" ::: "memory");
;             const unsigned og = xb_add(&bar[XB_TOP], 1u);
;             const unsigned tg = og / nx;
;             if (og + 1u == (tg + 1u) * nx) xb_add(&bar[XB_TOPGEN], 1u);
;             else XB_SPIN(xb_ld(&bar[XB_TOPGEN]) == tg, bar);
;             __builtin_amdgcn_fence(__ATOMIC_ACQUIRE, "agent");
;             xb_add(&bar[XB_XGEN(b.x)], 1u);
;             asm volatile("s_waitcnt vmcnt(0)" ::: "memory");
;         } else {
;             XB_SPIN(xb_ld(&bar[XB_XGEN(b.x)]) == gen, bar);
.LBB0_146:
	s_or_b64 exec, exec, s[6:7]
	v_cvt_f32_u32_e32 v4, v2
	s_waitcnt vmcnt(0)
	v_readfirstlane_b32 s4, v3
	v_sub_u32_e32 v3, 0, v2
	v_rcp_iflag_f32_e32 v4, v4
	v_add_u32_e32 v5, s4, v1
	v_mul_f32_e32 v4, 0x4f7ffffe, v4
	v_cvt_u32_f32_e32 v4, v4
	v_mul_lo_u32 v1, v3, v4
	v_mul_hi_u32 v1, v4, v1
	v_add_u32_e32 v1, v4, v1
	v_mul_hi_u32 v1, v5, v1
	v_mul_lo_u32 v3, v1, v2
	v_sub_u32_e32 v3, v5, v3
	v_add_u32_e32 v4, 1, v1
	v_cmp_ge_u32_e32 vcc, v3, v2
	s_nop 1
	v_cndmask_b32_e32 v1, v1, v4, vcc
	v_sub_u32_e32 v4, v3, v2
	v_cndmask_b32_e32 v3, v3, v4, vcc
	v_add_u32_e32 v4, 1, v1
	v_cmp_ge_u32_e32 vcc, v3, v2
	v_add_u32_e32 v3, 1, v5
	s_nop 0
	v_cndmask_b32_e32 v1, v1, v4, vcc
	v_mul_lo_u32 v4, v2, v1
	v_add_u32_e32 v2, v4, v2
	v_cmp_ne_u32_e32 vcc, v3, v2
	s_and_saveexec_b64 s[4:5], vcc
	s_xor_b64 s[4:5], exec, s[4:5]
	s_cbranch_execz .LBB0_160
	s_waitcnt lgkmcnt(0)
	v_mad_u32_u24 v1, v1, v0, v0
	v_readlane_b32 s10, v254, 8
	v_readlane_b32 s11, v254, 9
	v_mov_b32_e32 v0, 0
	s_add_u32 s10, s10, 0xfa03400
	s_addc_u32 s11, s11, 0
	global_load_dword v0, v0, s[10:11] sc1
	s_waitcnt vmcnt(0)
	v_cmp_gt_u32_e32 vcc, v1, v0
	s_and_saveexec_b64 s[6:7], vcc
	s_cbranch_execz .LBB0_159
	v_readlane_b32 s8, v254, 8
	v_readlane_b32 s9, v254, 9
	s_add_u32 s8, s8, 0xfa00200
	s_addc_u32 s9, s9, 0
	s_mov_b32 s22, 1
	s_mov_b64 s[12:13], 0
	v_mov_b32_e32 v0, 0
	s_branch .LBB0_150

; __device__ __forceinline__ unsigned xb_ld(unsigned* p)              { return __hip_atomic_load(p, __ATOMIC_RELAXED, __HIP_MEMORY_SCOPE_AGENT); }
; #define XB_SPIN(cond, bar) do { unsigned _sp = 0; while (cond) { __builtin_amdgcn_s_sleep(1); \
;     if ((++_sp & 255u) == 0u) { if (xb_ld(&(bar)[XB_TMO])) break; if (_sp > XB_SPIN_CAP) { atomicAdd(&(bar)[XB_TMO], 1u); break; } } } } while (0)
; __device__ __forceinline__ void xcd_barrier(const XcdBarrier& b) {
;     ...
;             XB_SPIN(xb_ld(&bar[XB_XGEN(b.x)]) == gen, bar);
.LBB0_154:
	global_load_dword v2, v0, s[10:11] sc1
	s_add_i32 s22, s22, 1
	s_mov_b64 s[18:19], -1
	s_waitcnt vmcnt(0)
	v_cmp_le_u32_e32 vcc, v1, v2
	s_orn2_b64 s[16:17], vcc, exec
	s_branch .LBB0_149

; __device__ __forceinline__ unsigned xb_ld(unsigned* p)              { return __hip_atomic_load(p, __ATOMIC_RELAXED, __HIP_MEMORY_SCOPE_AGENT); }
; __device__ __forceinline__ unsigned xb_add(unsigned* p, unsigned v) { return __hip_atomic_fetch_add(p, v, __ATOMIC_RELAXED, __HIP_MEMORY_SCOPE_AGENT); }
; #define XB_SPIN(cond, bar) do { unsigned _sp = 0; while (cond) { __builtin_amdgcn_s_sleep(1); \
;     if ((++_sp & 255u) == 0u) { if (xb_ld(&(bar)[XB_TMO])) break; if (_sp > XB_SPIN_CAP) { atomicAdd(&(bar)[XB_TMO], 1u); break; } } } } while (0)
; __device__ __forceinline__ void xcd_barrier(const XcdBarrier& b) {
;     ...
;             const unsigned og = xb_add(&bar[XB_TOP], 1u);
;             const unsigned tg = og / nx;
;             if (og + 1u == (tg + 1u) * nx) xb_add(&bar[XB_TOPGEN], 1u);
;             else XB_SPIN(xb_ld(&bar[XB_TOPGEN]) == tg, bar);
.LBB0_163:
	s_or_b64 exec, exec, s[6:7]
	v_cvt_f32_u32_e32 v3, v0
	s_waitcnt vmcnt(0)
	v_readfirstlane_b32 s4, v2
	s_mov_b64 s[8:9], -1
	v_rcp_iflag_f32_e32 v3, v3
	v_add_u32_e32 v1, s4, v1
	v_add_u32_e32 v4, 1, v1
	v_readlane_b32 s4, v254, 8
	v_mul_f32_e32 v2, 0x4f7ffffe, v3
	v_cvt_u32_f32_e32 v2, v2
	v_sub_u32_e32 v3, 0, v0
	v_readlane_b32 s5, v254, 9
	s_add_u32 s6, s4, 0xfa03500
	v_mul_lo_u32 v3, v3, v2
	v_mul_hi_u32 v3, v2, v3
	v_add_u32_e32 v2, v2, v3
	v_mul_hi_u32 v2, v1, v2
	v_mul_lo_u32 v3, v2, v0
	v_sub_u32_e32 v1, v1, v3
	v_add_u32_e32 v5, 1, v2
	v_cmp_ge_u32_e32 vcc, v1, v0
	v_sub_u32_e32 v3, v1, v0
	s_addc_u32 s7, s5, 0
	v_cndmask_b32_e32 v2, v2, v5, vcc
	v_cndmask_b32_e32 v1, v1, v3, vcc
	v_add_u32_e32 v3, 1, v2
	v_cmp_ge_u32_e32 vcc, v1, v0
	s_nop 1
	v_cndmask_b32_e32 v2, v2, v3, vcc
	v_mul_lo_u32 v1, v0, v2
	v_add_u32_e32 v0, v1, v0
	v_cmp_ne_u32_e32 vcc, v4, v0
	v_mov_b32_e32 v2, v0
	v_mov_b64_e32 v[0:1], s[6:7]
	s_and_saveexec_b64 s[4:5], vcc
	s_cbranch_execz .LBB0_175
	v_mov_b32_e32 v0, 0
	global_load_dword v1, v0, s[6:7] offset:-256 sc1
	s_mov_b64 s[12:13], 0
	s_waitcnt vmcnt(0)
	v_cmp_gt_u32_e32 vcc, v2, v1
	s_and_saveexec_b64 s[10:11], vcc
	s_cbranch_execz .LBB0_174
	v_readlane_b32 s8, v254, 8
	v_readlane_b32 s9, v254, 9
	s_add_u32 s8, s8, 0xfa00200
	s_addc_u32 s9, s9, 0
	s_mov_b32 s22, 1
	s_branch .LBB0_167

; __device__ __forceinline__ unsigned xb_ld(unsigned* p)              { return __hip_atomic_load(p, __ATOMIC_RELAXED, __HIP_MEMORY_SCOPE_AGENT); }
; #define XB_SPIN(cond, bar) do { unsigned _sp = 0; while (cond) { __builtin_amdgcn_s_sleep(1); \
;     if ((++_sp & 255u) == 0u) { if (xb_ld(&(bar)[XB_TMO])) break; if (_sp > XB_SPIN_CAP) { atomicAdd(&(bar)[XB_TMO], 1u); break; } } } } while (0)
; __device__ __forceinline__ void xcd_barrier(const XcdBarrier& b) {
;     ...
;             else XB_SPIN(xb_ld(&bar[XB_TOPGEN]) == tg, bar);
.LBB0_171:
	global_load_dword v1, v0, s[6:7] offset:-256 sc1
	s_add_i32 s22, s22, 1
	s_mov_b64 s[16:17], -1
	s_waitcnt vmcnt(0)
	v_cmp_le_u32_e32 vcc, v2, v1
	s_orn2_b64 s[20:21], vcc, exec
	s_branch .LBB0_166

; __device__ __forceinline__ unsigned xb_ld(unsigned* p)              { return __hip_atomic_load(p, __ATOMIC_RELAXED, __HIP_MEMORY_SCOPE_AGENT); }
; __device__ __forceinline__ unsigned xb_add(unsigned* p, unsigned v) { return __hip_atomic_fetch_add(p, v, __ATOMIC_RELAXED, __HIP_MEMORY_SCOPE_AGENT); }
; #define XB_SPIN(cond, bar) do { unsigned _sp = 0; while (cond) { __builtin_amdgcn_s_sleep(1); \
;     if ((++_sp & 255u) == 0u) { if (xb_ld(&(bar)[XB_TMO])) break; if (_sp > XB_SPIN_CAP) { atomicAdd(&(bar)[XB_TMO], 1u); break; } } } } while (0)
; __device__ __forceinline__ void xcd_barrier(const XcdBarrier& b) {
;     ...
;             const unsigned og = xb_add(&bar[XB_TOP], 1u);
;             const unsigned tg = og / nx;
;             if (og + 1u == (tg + 1u) * nx) xb_add(&bar[XB_TOPGEN], 1u);
;             else XB_SPIN(xb_ld(&bar[XB_TOPGEN]) == tg, bar);
.LBB0_379:
	s_or_b64 exec, exec, s[8:9]
	v_cvt_f32_u32_e32 v3, v0
	s_waitcnt vmcnt(0)
	v_readfirstlane_b32 s6, v2
	s_mov_b64 s[10:11], -1
	v_rcp_iflag_f32_e32 v3, v3
	v_add_u32_e32 v1, s6, v1
	v_add_u32_e32 v4, 1, v1
	v_readlane_b32 s6, v254, 8
	v_mul_f32_e32 v2, 0x4f7ffffe, v3
	v_cvt_u32_f32_e32 v2, v2
	v_sub_u32_e32 v3, 0, v0
	v_readlane_b32 s7, v254, 9
	s_add_u32 s8, s6, 0xfa03500
	v_mul_lo_u32 v3, v3, v2
	v_mul_hi_u32 v3, v2, v3
	v_add_u32_e32 v2, v2, v3
	v_mul_hi_u32 v2, v1, v2
	v_mul_lo_u32 v3, v2, v0
	v_sub_u32_e32 v1, v1, v3
	v_add_u32_e32 v5, 1, v2
	v_cmp_ge_u32_e32 vcc, v1, v0
	v_sub_u32_e32 v3, v1, v0
	s_addc_u32 s9, s7, 0
	v_cndmask_b32_e32 v2, v2, v5, vcc
	v_cndmask_b32_e32 v1, v1, v3, vcc
	v_add_u32_e32 v3, 1, v2
	v_cmp_ge_u32_e32 vcc, v1, v0
	s_nop 1
	v_cndmask_b32_e32 v2, v2, v3, vcc
	v_mul_lo_u32 v1, v0, v2
	v_add_u32_e32 v0, v1, v0
	v_cmp_ne_u32_e32 vcc, v4, v0
	v_mov_b32_e32 v2, v0
	v_mov_b64_e32 v[0:1], s[8:9]
	s_and_saveexec_b64 s[6:7], vcc
	s_cbranch_execz .LBB0_391
	v_mov_b32_e32 v0, 0
	global_load_dword v1, v0, s[8:9] offset:-256 sc1
	s_mov_b64 s[14:15], 0
	s_waitcnt vmcnt(0)
	v_cmp_gt_u32_e32 vcc, v2, v1
	s_and_saveexec_b64 s[12:13], vcc
	s_cbranch_execz .LBB0_390
	v_readlane_b32 s10, v254, 8
	v_readlane_b32 s11, v254, 9
	s_add_u32 s10, s10, 0xfa00200
	s_addc_u32 s11, s11, 0
	s_mov_b32 s24, 1
	s_branch .LBB0_383

; __device__ __forceinline__ unsigned xb_ld(unsigned* p)              { return __hip_atomic_load(p, __ATOMIC_RELAXED, __HIP_MEMORY_SCOPE_AGENT); }
; #define XB_SPIN(cond, bar) do { unsigned _sp = 0; while (cond) { __builtin_amdgcn_s_sleep(1); \
;     if ((++_sp & 255u) == 0u) { if (xb_ld(&(bar)[XB_TMO])) break; if (_sp > XB_SPIN_CAP) { atomicAdd(&(bar)[XB_TMO], 1u); break; } } } } while (0)
; __device__ __forceinline__ void xcd_barrier(const XcdBarrier& b) {
;     ...
;             else XB_SPIN(xb_ld(&bar[XB_TOPGEN]) == tg, bar);
.LBB0_387:
	global_load_dword v1, v0, s[8:9] offset:-256 sc1
	s_add_i32 s24, s24, 1
	s_mov_b64 s[18:19], -1
	s_waitcnt vmcnt(0)
	v_cmp_le_u32_e32 vcc, v2, v1
	s_orn2_b64 s[22:23], vcc, exec
	s_branch .LBB0_382

; __device__ __forceinline__ unsigned xb_ld(unsigned* p)              { return __hip_atomic_load(p, __ATOMIC_RELAXED, __HIP_MEMORY_SCOPE_AGENT); }
; __device__ __forceinline__ unsigned xb_add(unsigned* p, unsigned v) { return __hip_atomic_fetch_add(p, v, __ATOMIC_RELAXED, __HIP_MEMORY_SCOPE_AGENT); }
; #define XB_SPIN(cond, bar) do { unsigned _sp = 0; while (cond) { __builtin_amdgcn_s_sleep(1); \
;     if ((++_sp & 255u) == 0u) { if (xb_ld(&(bar)[XB_TMO])) break; if (_sp > XB_SPIN_CAP) { atomicAdd(&(bar)[XB_TMO], 1u); break; } } } } while (0)
; __device__ __forceinline__ void xcd_barrier(const XcdBarrier& b) {
;     ...
;         const unsigned old = xb_add(&bar[XB_XSUB(b.x)], 1u);
;         const unsigned gen = old / nloc;
;         if (old + 1u == (gen + 1u) * nloc) {
;             __builtin_amdgcn_fence(__ATOMIC_RELEASE, "agent");
;             asm volatile("s_waitcnt vmcnt(0)" ::: "memory");
;             const unsigned og = xb_add(&bar[XB_TOP], 1u);
;             const unsigned tg = og / nx;
;             if (og + 1u == (tg + 1u) * nx) xb_add(&bar[XB_TOPGEN], 1u);
;             else XB_SPIN(xb_ld(&bar[XB_TOPGEN]) == tg, bar);
;             __builtin_amdgcn_fence(__ATOMIC_ACQUIRE, "agent");
;             xb_add(&bar[XB_XGEN(b.x)], 1u);
;             asm volatile("s_waitcnt vmcnt(0)" ::: "memory");
;         } else {
;             XB_SPIN(xb_ld(&bar[XB_XGEN(b.x)]) == gen, bar);
.LBB0_2294:
	s_or_b64 exec, exec, s[8:9]
	v_cvt_f32_u32_e32 v4, v2
	s_waitcnt vmcnt(0)
	v_readfirstlane_b32 s6, v3
	v_sub_u32_e32 v3, 0, v2
	v_rcp_iflag_f32_e32 v4, v4
	v_add_u32_e32 v5, s6, v1
	v_mul_f32_e32 v4, 0x4f7ffffe, v4
	v_cvt_u32_f32_e32 v4, v4
	v_mul_lo_u32 v1, v3, v4
	v_mul_hi_u32 v1, v4, v1
	v_add_u32_e32 v1, v4, v1
	v_mul_hi_u32 v1, v5, v1
	v_mul_lo_u32 v3, v1, v2
	v_sub_u32_e32 v3, v5, v3
	v_add_u32_e32 v4, 1, v1
	v_cmp_ge_u32_e32 vcc, v3, v2
	s_nop 1
	v_cndmask_b32_e32 v1, v1, v4, vcc
	v_sub_u32_e32 v4, v3, v2
	v_cndmask_b32_e32 v3, v3, v4, vcc
	v_add_u32_e32 v4, 1, v1
	v_cmp_ge_u32_e32 vcc, v3, v2
	v_add_u32_e32 v3, 1, v5
	s_nop 0
	v_cndmask_b32_e32 v1, v1, v4, vcc
	v_mul_lo_u32 v4, v2, v1
	v_add_u32_e32 v2, v4, v2
	v_cmp_ne_u32_e32 vcc, v3, v2
	s_and_saveexec_b64 s[6:7], vcc
	s_xor_b64 s[6:7], exec, s[6:7]
	s_cbranch_execz .LBB0_2308
	s_waitcnt lgkmcnt(0)
	v_mad_u32_u24 v1, v1, v0, v0
	v_readlane_b32 s12, v254, 8
	v_readlane_b32 s13, v254, 9
	v_mov_b32_e32 v0, 0
	s_add_u32 s12, s12, 0xfa03400
	s_addc_u32 s13, s13, 0
	global_load_dword v0, v0, s[12:13] sc1
	s_waitcnt vmcnt(0)
	v_cmp_gt_u32_e32 vcc, v1, v0
	s_and_saveexec_b64 s[8:9], vcc
	s_cbranch_execz .LBB0_2307
	v_readlane_b32 s10, v254, 8
	v_readlane_b32 s11, v254, 9
	s_add_u32 s10, s10, 0xfa00200
	s_addc_u32 s11, s11, 0
	s_mov_b32 s24, 1
	s_mov_b64 s[14:15], 0
	v_mov_b32_e32 v0, 0
	s_branch .LBB0_2298

; __device__ __forceinline__ unsigned xb_ld(unsigned* p)              { return __hip_atomic_load(p, __ATOMIC_RELAXED, __HIP_MEMORY_SCOPE_AGENT); }
; #define XB_SPIN(cond, bar) do { unsigned _sp = 0; while (cond) { __builtin_amdgcn_s_sleep(1); \
;     if ((++_sp & 255u) == 0u) { if (xb_ld(&(bar)[XB_TMO])) break; if (_sp > XB_SPIN_CAP) { atomicAdd(&(bar)[XB_TMO], 1u); break; } } } } while (0)
; __device__ __forceinline__ void xcd_barrier(const XcdBarrier& b) {
;     ...
;             XB_SPIN(xb_ld(&bar[XB_XGEN(b.x)]) == gen, bar);
.LBB0_2302:
	global_load_dword v2, v0, s[12:13] sc1
	s_add_i32 s24, s24, 1
	s_mov_b64 s[20:21], -1
	s_waitcnt vmcnt(0)
	v_cmp_le_u32_e32 vcc, v1, v2
	s_orn2_b64 s[18:19], vcc, exec
	s_branch .LBB0_2297

; __device__ __forceinline__ unsigned xb_add(unsigned* p, unsigned v) { return __hip_atomic_fetch_add(p, v, __ATOMIC_RELAXED, __HIP_MEMORY_SCOPE_AGENT); }
; __device__ __forceinline__ void xcd_barrier(const XcdBarrier& b) {
;     ...
;             __builtin_amdgcn_fence(__ATOMIC_ACQUIRE, "agent");
;             xb_add(&bar[XB_XGEN(b.x)], 1u);
;             asm volatile("s_waitcnt vmcnt(0)" ::: "memory");
.LBB0_2573:
	s_or_b64 exec, exec, s[6:7]
	s_mov_b64 s[6:7], exec
	v_mbcnt_lo_u32_b32 v0, s6, 0
	v_mbcnt_hi_u32_b32 v0, s7, v0
	v_cmp_eq_u32_e32 vcc, 0, v0
	s_waitcnt vmcnt(0)
	buffer_inv sc1
	s_and_saveexec_b64 s[8:9], vcc
	s_cbranch_execz .LBB0_2575
	s_bcnt1_i32_b64 s6, s[6:7]
	v_mov_b32_e32 v0, 0x2000
	v_mov_b32_e32 v1, s6
	global_atomic_add v0, v1, s[2:3] offset:1024
	s_nop 0
	s_nop 0
	s_nop 0
	s_nop 0
	s_nop 0
	s_nop 0
	s_nop 0
	s_nop 0
	s_nop 0
	s_nop 0
	s_nop 0
	s_nop 0
	s_nop 0
	s_nop 0
	s_nop 0
	s_nop 0
	s_nop 0
	s_nop 0
	s_nop 0
	s_nop 0
	s_nop 0
	s_nop 0
	s_nop 0
	s_nop 0
	s_nop 0
	s_nop 0
	s_nop 0
	s_nop 0
	s_nop 0
	s_nop 0
	s_nop 0
	s_nop 0
	s_nop 0
.LBB0_2575:
	s_or_b64 exec, exec, s[8:9]
	s_waitcnt vmcnt(0)
